# prompt adaLN epilogue: dt/forget weight vectors staged in LDS once per layer (were re-read from L2 per token), full-wave sums by DPP instead of ds_bpermute chains
# speedup vs baseline: 1.1027x; 1.0307x over previous
;     ...
;     for (int j0 = 0; j0 < NTL * 16; j0 += 16) {
;         u32x4_t w[16]; float cj[16];
; #pragma unroll
;         for (int jj = 0; jj < 16; ++jj) { const u32x2_t pr = pl[j0 + jj]; const int ej = __builtin_amdgcn_readfirstlane((int)pr.x); cj[jj] = __uint_as_float(pr.y);
;             w[jj] = *(const u32x4_t*)(v8 + (size_t)ej * D + 16 * lane); }
; #pragma unroll
;         for (int jj = 0; jj < 16; ++jj) { const float c = cj[jj];
; #pragma unroll
;             for (int q = 0; q < 4; ++q) { const f32x2_t lo = __builtin_amdgcn_cvt_pk_f32_fp8((int)w[jj][q], false), hi = __builtin_amdgcn_cvt_pk_f32_fp8((int)w[jj][q], true);
;                 o[4 * q] += c * lo[0]; o[4 * q + 1] += c * lo[1]; o[4 * q + 2] += c * hi[0]; o[4 * q + 3] += c * hi[1]; } }
.Lg2_loop:
	s_and_b32 s9, s22, 7
	s_lshr_b32 s10, s22, 3
	s_mul_i32 s11, s9, s20
	s_lshl_b32 s23, s10, 9
	s_add_u32 s14, s58, s11
	s_addc_u32 s15, s59, 0
	s_add_u32 s14, s14, s23
	s_addc_u32 s15, s15, 0
	s_mul_i32 s11, s9, s34
	s_add_u32 s11, s11, s48
	s_lshr_b32 s11, s11, 13
	s_mul_i32 s11, s11, 0x6000
	s_add_u32 s16, s60, s11
	s_addc_u32 s17, s61, 0
	s_add_u32 s16, s16, s23
	s_addc_u32 s17, s17, 0
	global_load_dwordx2 v[58:59], v6, s[14:15]
	global_load_dwordx2 v[60:61], v6, s[16:17]
	s_lshl_b32 s9, s9, 10
	v_add_u32_e32 v7, s9, v5
	s_add_u32 s10, s22, 1
	s_and_b32 s9, s10, 7
	s_lshl_b32 s9, s9, 10
	v_add_u32_e32 v8, s9, v5
	s_lshr_b32 s10, s10, 3
	s_lshl_b32 s10, s10, 7
	s_add_u32 s12, s56, s10
	s_addc_u32 s13, s57, 0
	ds_read_b128 v[84:87], v7 offset:0
	ds_read_b128 v[88:91], v7 offset:16
	ds_read_b128 v[92:95], v7 offset:32
	ds_read_b128 v[96:99], v7 offset:48
	ds_read_b128 v[104:107], v7 offset:64
	ds_read_b128 v[108:111], v7 offset:80
	ds_read_b128 v[112:115], v7 offset:96
	ds_read_b128 v[180:183], v7 offset:112
	ds_read_b128 v[26:29], v8 offset:0
	ds_read_b128 v[30:33], v8 offset:16
	ds_read_b128 v[34:37], v8 offset:32
	ds_read_b128 v[38:41], v8 offset:48
	ds_read_b128 v[42:45], v8 offset:64
	ds_read_b128 v[46:49], v8 offset:80
	ds_read_b128 v[50:53], v8 offset:96
	ds_read_b128 v[54:57], v8 offset:112
	s_waitcnt lgkmcnt(0)
	v_lshl_add_u32 v68, v26, 10, v4
	v_lshl_add_u32 v69, v28, 10, v4
	v_lshl_add_u32 v70, v30, 10, v4
	v_lshl_add_u32 v71, v32, 10, v4
	v_lshl_add_u32 v72, v34, 10, v4
	v_lshl_add_u32 v73, v36, 10, v4
	v_lshl_add_u32 v74, v38, 10, v4
	v_lshl_add_u32 v75, v40, 10, v4
	v_lshl_add_u32 v76, v42, 10, v4
	v_lshl_add_u32 v77, v44, 10, v4
	v_lshl_add_u32 v78, v46, 10, v4
	v_lshl_add_u32 v79, v48, 10, v4
	v_lshl_add_u32 v80, v50, 10, v4
	v_lshl_add_u32 v81, v52, 10, v4
	v_lshl_add_u32 v82, v54, 10, v4
	v_lshl_add_u32 v83, v56, 10, v4
	s_waitcnt vmcnt(16)
	v_cvt_pk_f32_fp8_e32 v[26:27], v120
	v_cvt_pk_f32_fp8_sdwa v[28:29], v120 src0_sel:WORD_1
	v_cvt_pk_f32_fp8_e32 v[30:31], v121
	v_cvt_pk_f32_fp8_sdwa v[32:33], v121 src0_sel:WORD_1
	v_cvt_pk_f32_fp8_e32 v[34:35], v122
	v_cvt_pk_f32_fp8_sdwa v[36:37], v122 src0_sel:WORD_1
	v_cvt_pk_f32_fp8_e32 v[38:39], v123
	v_cvt_pk_f32_fp8_sdwa v[40:41], v123 src0_sel:WORD_1
	v_cvt_pk_f32_fp8_e32 v[42:43], v124
	v_cvt_pk_f32_fp8_sdwa v[44:45], v124 src0_sel:WORD_1
	v_cvt_pk_f32_fp8_e32 v[46:47], v125
	v_cvt_pk_f32_fp8_sdwa v[48:49], v125 src0_sel:WORD_1
	v_cvt_pk_f32_fp8_e32 v[50:51], v126
	v_cvt_pk_f32_fp8_sdwa v[52:53], v126 src0_sel:WORD_1
	v_cvt_pk_f32_fp8_e32 v[54:55], v127
	v_cvt_pk_f32_fp8_sdwa v[56:57], v127 src0_sel:WORD_1
	global_load_dwordx4 v[120:123], v68, s[12:13]
	global_load_dwordx4 v[124:127], v69, s[12:13]
	v_pk_mul_f32 v[10:11], v[84:85], v[26:27] op_sel:[1,0]
	v_pk_mul_f32 v[12:13], v[84:85], v[28:29] op_sel:[1,0]
	v_pk_mul_f32 v[14:15], v[84:85], v[30:31] op_sel:[1,0]
	v_pk_mul_f32 v[16:17], v[84:85], v[32:33] op_sel:[1,0]
	v_pk_mul_f32 v[18:19], v[84:85], v[34:35] op_sel:[1,0]
	v_pk_mul_f32 v[20:21], v[84:85], v[36:37] op_sel:[1,0]
	v_pk_mul_f32 v[22:23], v[84:85], v[38:39] op_sel:[1,0]
	v_pk_mul_f32 v[24:25], v[84:85], v[40:41] op_sel:[1,0]
	v_pk_fma_f32 v[10:11], v[86:87], v[42:43], v[10:11] op_sel:[1,0,0]
	v_pk_fma_f32 v[12:13], v[86:87], v[44:45], v[12:13] op_sel:[1,0,0]
	v_pk_fma_f32 v[14:15], v[86:87], v[46:47], v[14:15] op_sel:[1,0,0]
	v_pk_fma_f32 v[16:17], v[86:87], v[48:49], v[16:17] op_sel:[1,0,0]
	v_pk_fma_f32 v[18:19], v[86:87], v[50:51], v[18:19] op_sel:[1,0,0]
	v_pk_fma_f32 v[20:21], v[86:87], v[52:53], v[20:21] op_sel:[1,0,0]
	v_pk_fma_f32 v[22:23], v[86:87], v[54:55], v[22:23] op_sel:[1,0,0]
	v_pk_fma_f32 v[24:25], v[86:87], v[56:57], v[24:25] op_sel:[1,0,0]
	s_waitcnt vmcnt(16)
	v_cvt_pk_f32_fp8_e32 v[26:27], v128
	v_cvt_pk_f32_fp8_sdwa v[28:29], v128 src0_sel:WORD_1
	v_cvt_pk_f32_fp8_e32 v[30:31], v129
	v_cvt_pk_f32_fp8_sdwa v[32:33], v129 src0_sel:WORD_1
	v_cvt_pk_f32_fp8_e32 v[34:35], v130
	v_cvt_pk_f32_fp8_sdwa v[36:37], v130 src0_sel:WORD_1
	v_cvt_pk_f32_fp8_e32 v[38:39], v131
	v_cvt_pk_f32_fp8_sdwa v[40:41], v131 src0_sel:WORD_1
	v_cvt_pk_f32_fp8_e32 v[42:43], v132
	v_cvt_pk_f32_fp8_sdwa v[44:45], v132 src0_sel:WORD_1
	v_cvt_pk_f32_fp8_e32 v[46:47], v133
	v_cvt_pk_f32_fp8_sdwa v[48:49], v133 src0_sel:WORD_1
	v_cvt_pk_f32_fp8_e32 v[50:51], v134
	v_cvt_pk_f32_fp8_sdwa v[52:53], v134 src0_sel:WORD_1
	v_cvt_pk_f32_fp8_e32 v[54:55], v135
	v_cvt_pk_f32_fp8_sdwa v[56:57], v135 src0_sel:WORD_1
	global_load_dwordx4 v[128:131], v70, s[12:13]
	global_load_dwordx4 v[132:135], v71, s[12:13]
	v_pk_fma_f32 v[10:11], v[88:89], v[26:27], v[10:11] op_sel:[1,0,0]
	v_pk_fma_f32 v[12:13], v[88:89], v[28:29], v[12:13] op_sel:[1,0,0]
	v_pk_fma_f32 v[14:15], v[88:89], v[30:31], v[14:15] op_sel:[1,0,0]
	v_pk_fma_f32 v[16:17], v[88:89], v[32:33], v[16:17] op_sel:[1,0,0]
	v_pk_fma_f32 v[18:19], v[88:89], v[34:35], v[18:19] op_sel:[1,0,0]
	v_pk_fma_f32 v[20:21], v[88:89], v[36:37], v[20:21] op_sel:[1,0,0]
	v_pk_fma_f32 v[22:23], v[88:89], v[38:39], v[22:23] op_sel:[1,0,0]
	v_pk_fma_f32 v[24:25], v[88:89], v[40:41], v[24:25] op_sel:[1,0,0]
	v_pk_fma_f32 v[10:11], v[90:91], v[42:43], v[10:11] op_sel:[1,0,0]
	v_pk_fma_f32 v[12:13], v[90:91], v[44:45], v[12:13] op_sel:[1,0,0]
	v_pk_fma_f32 v[14:15], v[90:91], v[46:47], v[14:15] op_sel:[1,0,0]
	v_pk_fma_f32 v[16:17], v[90:91], v[48:49], v[16:17] op_sel:[1,0,0]
	v_pk_fma_f32 v[18:19], v[90:91], v[50:51], v[18:19] op_sel:[1,0,0]
	v_pk_fma_f32 v[20:21], v[90:91], v[52:53], v[20:21] op_sel:[1,0,0]
	v_pk_fma_f32 v[22:23], v[90:91], v[54:55], v[22:23] op_sel:[1,0,0]
	v_pk_fma_f32 v[24:25], v[90:91], v[56:57], v[24:25] op_sel:[1,0,0]
	s_waitcnt vmcnt(16)
;     ...
;         for (int jj = 0; jj < 16; ++jj) { const u32x2_t pr = pl[j0 + jj]; const int ej = __builtin_amdgcn_readfirstlane((int)pr.x); cj[jj] = __uint_as_float(pr.y);
;             w[jj] = *(const u32x4_t*)(v8 + (size_t)ej * D + 16 * lane); }
; #pragma unroll
;         for (int jj = 0; jj < 16; ++jj) { const float c = cj[jj];
; #pragma unroll
;             for (int q = 0; q < 4; ++q) { const f32x2_t lo = __builtin_amdgcn_cvt_pk_f32_fp8((int)w[jj][q], false), hi = __builtin_amdgcn_cvt_pk_f32_fp8((int)w[jj][q], true);
;                 o[4 * q] += c * lo[0]; o[4 * q + 1] += c * lo[1]; o[4 * q + 2] += c * hi[0]; o[4 * q + 3] += c * hi[1]; } }
	v_cvt_pk_f32_fp8_e32 v[26:27], v136
	v_cvt_pk_f32_fp8_sdwa v[28:29], v136 src0_sel:WORD_1
	v_cvt_pk_f32_fp8_e32 v[30:31], v137
	v_cvt_pk_f32_fp8_sdwa v[32:33], v137 src0_sel:WORD_1
	v_cvt_pk_f32_fp8_e32 v[34:35], v138
	v_cvt_pk_f32_fp8_sdwa v[36:37], v138 src0_sel:WORD_1
	v_cvt_pk_f32_fp8_e32 v[38:39], v139
	v_cvt_pk_f32_fp8_sdwa v[40:41], v139 src0_sel:WORD_1
	v_cvt_pk_f32_fp8_e32 v[42:43], v140
	v_cvt_pk_f32_fp8_sdwa v[44:45], v140 src0_sel:WORD_1
	v_cvt_pk_f32_fp8_e32 v[46:47], v141
	v_cvt_pk_f32_fp8_sdwa v[48:49], v141 src0_sel:WORD_1
	v_cvt_pk_f32_fp8_e32 v[50:51], v142
	v_cvt_pk_f32_fp8_sdwa v[52:53], v142 src0_sel:WORD_1
	v_cvt_pk_f32_fp8_e32 v[54:55], v143
	v_cvt_pk_f32_fp8_sdwa v[56:57], v143 src0_sel:WORD_1
	global_load_dwordx4 v[136:139], v72, s[12:13]
	global_load_dwordx4 v[140:143], v73, s[12:13]
	v_pk_fma_f32 v[10:11], v[92:93], v[26:27], v[10:11] op_sel:[1,0,0]
	v_pk_fma_f32 v[12:13], v[92:93], v[28:29], v[12:13] op_sel:[1,0,0]
	v_pk_fma_f32 v[14:15], v[92:93], v[30:31], v[14:15] op_sel:[1,0,0]
	v_pk_fma_f32 v[16:17], v[92:93], v[32:33], v[16:17] op_sel:[1,0,0]
	v_pk_fma_f32 v[18:19], v[92:93], v[34:35], v[18:19] op_sel:[1,0,0]
	v_pk_fma_f32 v[20:21], v[92:93], v[36:37], v[20:21] op_sel:[1,0,0]
	v_pk_fma_f32 v[22:23], v[92:93], v[38:39], v[22:23] op_sel:[1,0,0]
	v_pk_fma_f32 v[24:25], v[92:93], v[40:41], v[24:25] op_sel:[1,0,0]
	v_pk_fma_f32 v[10:11], v[94:95], v[42:43], v[10:11] op_sel:[1,0,0]
	v_pk_fma_f32 v[12:13], v[94:95], v[44:45], v[12:13] op_sel:[1,0,0]
	v_pk_fma_f32 v[14:15], v[94:95], v[46:47], v[14:15] op_sel:[1,0,0]
	v_pk_fma_f32 v[16:17], v[94:95], v[48:49], v[16:17] op_sel:[1,0,0]
	v_pk_fma_f32 v[18:19], v[94:95], v[50:51], v[18:19] op_sel:[1,0,0]
	v_pk_fma_f32 v[20:21], v[94:95], v[52:53], v[20:21] op_sel:[1,0,0]
	v_pk_fma_f32 v[22:23], v[94:95], v[54:55], v[22:23] op_sel:[1,0,0]
	v_pk_fma_f32 v[24:25], v[94:95], v[56:57], v[24:25] op_sel:[1,0,0]
	s_waitcnt vmcnt(16)
	v_cvt_pk_f32_fp8_e32 v[26:27], v144
	v_cvt_pk_f32_fp8_sdwa v[28:29], v144 src0_sel:WORD_1
	v_cvt_pk_f32_fp8_e32 v[30:31], v145
	v_cvt_pk_f32_fp8_sdwa v[32:33], v145 src0_sel:WORD_1
	v_cvt_pk_f32_fp8_e32 v[34:35], v146
	v_cvt_pk_f32_fp8_sdwa v[36:37], v146 src0_sel:WORD_1
	v_cvt_pk_f32_fp8_e32 v[38:39], v147
	v_cvt_pk_f32_fp8_sdwa v[40:41], v147 src0_sel:WORD_1
	v_cvt_pk_f32_fp8_e32 v[42:43], v148
	v_cvt_pk_f32_fp8_sdwa v[44:45], v148 src0_sel:WORD_1
	v_cvt_pk_f32_fp8_e32 v[46:47], v149
	v_cvt_pk_f32_fp8_sdwa v[48:49], v149 src0_sel:WORD_1
	v_cvt_pk_f32_fp8_e32 v[50:51], v150
	v_cvt_pk_f32_fp8_sdwa v[52:53], v150 src0_sel:WORD_1
	v_cvt_pk_f32_fp8_e32 v[54:55], v151
	v_cvt_pk_f32_fp8_sdwa v[56:57], v151 src0_sel:WORD_1
	global_load_dwordx4 v[144:147], v74, s[12:13]
	global_load_dwordx4 v[148:151], v75, s[12:13]
	v_pk_fma_f32 v[10:11], v[96:97], v[26:27], v[10:11] op_sel:[1,0,0]
	v_pk_fma_f32 v[12:13], v[96:97], v[28:29], v[12:13] op_sel:[1,0,0]
	v_pk_fma_f32 v[14:15], v[96:97], v[30:31], v[14:15] op_sel:[1,0,0]
	v_pk_fma_f32 v[16:17], v[96:97], v[32:33], v[16:17] op_sel:[1,0,0]
	v_pk_fma_f32 v[18:19], v[96:97], v[34:35], v[18:19] op_sel:[1,0,0]
	v_pk_fma_f32 v[20:21], v[96:97], v[36:37], v[20:21] op_sel:[1,0,0]
	v_pk_fma_f32 v[22:23], v[96:97], v[38:39], v[22:23] op_sel:[1,0,0]
	v_pk_fma_f32 v[24:25], v[96:97], v[40:41], v[24:25] op_sel:[1,0,0]
	v_pk_fma_f32 v[10:11], v[98:99], v[42:43], v[10:11] op_sel:[1,0,0]
	v_pk_fma_f32 v[12:13], v[98:99], v[44:45], v[12:13] op_sel:[1,0,0]
	v_pk_fma_f32 v[14:15], v[98:99], v[46:47], v[14:15] op_sel:[1,0,0]
	v_pk_fma_f32 v[16:17], v[98:99], v[48:49], v[16:17] op_sel:[1,0,0]
	v_pk_fma_f32 v[18:19], v[98:99], v[50:51], v[18:19] op_sel:[1,0,0]
	v_pk_fma_f32 v[20:21], v[98:99], v[52:53], v[20:21] op_sel:[1,0,0]
	v_pk_fma_f32 v[22:23], v[98:99], v[54:55], v[22:23] op_sel:[1,0,0]
	v_pk_fma_f32 v[24:25], v[98:99], v[56:57], v[24:25] op_sel:[1,0,0]
	s_waitcnt vmcnt(16)
	v_cvt_pk_f32_fp8_e32 v[26:27], v152
	v_cvt_pk_f32_fp8_sdwa v[28:29], v152 src0_sel:WORD_1
	v_cvt_pk_f32_fp8_e32 v[30:31], v153
	v_cvt_pk_f32_fp8_sdwa v[32:33], v153 src0_sel:WORD_1
	v_cvt_pk_f32_fp8_e32 v[34:35], v154
	v_cvt_pk_f32_fp8_sdwa v[36:37], v154 src0_sel:WORD_1
	v_cvt_pk_f32_fp8_e32 v[38:39], v155
	v_cvt_pk_f32_fp8_sdwa v[40:41], v155 src0_sel:WORD_1
	v_cvt_pk_f32_fp8_e32 v[42:43], v156
	v_cvt_pk_f32_fp8_sdwa v[44:45], v156 src0_sel:WORD_1
	v_cvt_pk_f32_fp8_e32 v[46:47], v157
	v_cvt_pk_f32_fp8_sdwa v[48:49], v157 src0_sel:WORD_1
	v_cvt_pk_f32_fp8_e32 v[50:51], v158
	v_cvt_pk_f32_fp8_sdwa v[52:53], v158 src0_sel:WORD_1
	v_cvt_pk_f32_fp8_e32 v[54:55], v159
	v_cvt_pk_f32_fp8_sdwa v[56:57], v159 src0_sel:WORD_1
	global_load_dwordx4 v[152:155], v76, s[12:13]
	global_load_dwordx4 v[156:159], v77, s[12:13]
	v_pk_fma_f32 v[10:11], v[104:105], v[26:27], v[10:11] op_sel:[1,0,0]
	v_pk_fma_f32 v[12:13], v[104:105], v[28:29], v[12:13] op_sel:[1,0,0]
	v_pk_fma_f32 v[14:15], v[104:105], v[30:31], v[14:15] op_sel:[1,0,0]
	v_pk_fma_f32 v[16:17], v[104:105], v[32:33], v[16:17] op_sel:[1,0,0]
	v_pk_fma_f32 v[18:19], v[104:105], v[34:35], v[18:19] op_sel:[1,0,0]
	v_pk_fma_f32 v[20:21], v[104:105], v[36:37], v[20:21] op_sel:[1,0,0]
	v_pk_fma_f32 v[22:23], v[104:105], v[38:39], v[22:23] op_sel:[1,0,0]
	v_pk_fma_f32 v[24:25], v[104:105], v[40:41], v[24:25] op_sel:[1,0,0]
	v_pk_fma_f32 v[10:11], v[106:107], v[42:43], v[10:11] op_sel:[1,0,0]
	v_pk_fma_f32 v[12:13], v[106:107], v[44:45], v[12:13] op_sel:[1,0,0]
	v_pk_fma_f32 v[14:15], v[106:107], v[46:47], v[14:15] op_sel:[1,0,0]
	v_pk_fma_f32 v[16:17], v[106:107], v[48:49], v[16:17] op_sel:[1,0,0]
	v_pk_fma_f32 v[18:19], v[106:107], v[50:51], v[18:19] op_sel:[1,0,0]
	v_pk_fma_f32 v[20:21], v[106:107], v[52:53], v[20:21] op_sel:[1,0,0]
	v_pk_fma_f32 v[22:23], v[106:107], v[54:55], v[22:23] op_sel:[1,0,0]
	v_pk_fma_f32 v[24:25], v[106:107], v[56:57], v[24:25] op_sel:[1,0,0]
	s_waitcnt vmcnt(16)
;     ...
;         for (int jj = 0; jj < 16; ++jj) { const u32x2_t pr = pl[j0 + jj]; const int ej = __builtin_amdgcn_readfirstlane((int)pr.x); cj[jj] = __uint_as_float(pr.y);
;             w[jj] = *(const u32x4_t*)(v8 + (size_t)ej * D + 16 * lane); }
; #pragma unroll
;         for (int jj = 0; jj < 16; ++jj) { const float c = cj[jj];
; #pragma unroll
;             for (int q = 0; q < 4; ++q) { const f32x2_t lo = __builtin_amdgcn_cvt_pk_f32_fp8((int)w[jj][q], false), hi = __builtin_amdgcn_cvt_pk_f32_fp8((int)w[jj][q], true);
;                 o[4 * q] += c * lo[0]; o[4 * q + 1] += c * lo[1]; o[4 * q + 2] += c * hi[0]; o[4 * q + 3] += c * hi[1]; } }
	v_cvt_pk_f32_fp8_e32 v[26:27], v160
	v_cvt_pk_f32_fp8_sdwa v[28:29], v160 src0_sel:WORD_1
	v_cvt_pk_f32_fp8_e32 v[30:31], v161
	v_cvt_pk_f32_fp8_sdwa v[32:33], v161 src0_sel:WORD_1
	v_cvt_pk_f32_fp8_e32 v[34:35], v162
	v_cvt_pk_f32_fp8_sdwa v[36:37], v162 src0_sel:WORD_1
	v_cvt_pk_f32_fp8_e32 v[38:39], v163
	v_cvt_pk_f32_fp8_sdwa v[40:41], v163 src0_sel:WORD_1
	v_cvt_pk_f32_fp8_e32 v[42:43], v164
	v_cvt_pk_f32_fp8_sdwa v[44:45], v164 src0_sel:WORD_1
	v_cvt_pk_f32_fp8_e32 v[46:47], v165
	v_cvt_pk_f32_fp8_sdwa v[48:49], v165 src0_sel:WORD_1
	v_cvt_pk_f32_fp8_e32 v[50:51], v166
	v_cvt_pk_f32_fp8_sdwa v[52:53], v166 src0_sel:WORD_1
	v_cvt_pk_f32_fp8_e32 v[54:55], v167
	v_cvt_pk_f32_fp8_sdwa v[56:57], v167 src0_sel:WORD_1
	global_load_dwordx4 v[160:163], v78, s[12:13]
	global_load_dwordx4 v[164:167], v79, s[12:13]
	v_pk_fma_f32 v[10:11], v[108:109], v[26:27], v[10:11] op_sel:[1,0,0]
	v_pk_fma_f32 v[12:13], v[108:109], v[28:29], v[12:13] op_sel:[1,0,0]
	v_pk_fma_f32 v[14:15], v[108:109], v[30:31], v[14:15] op_sel:[1,0,0]
	v_pk_fma_f32 v[16:17], v[108:109], v[32:33], v[16:17] op_sel:[1,0,0]
	v_pk_fma_f32 v[18:19], v[108:109], v[34:35], v[18:19] op_sel:[1,0,0]
	v_pk_fma_f32 v[20:21], v[108:109], v[36:37], v[20:21] op_sel:[1,0,0]
	v_pk_fma_f32 v[22:23], v[108:109], v[38:39], v[22:23] op_sel:[1,0,0]
	v_pk_fma_f32 v[24:25], v[108:109], v[40:41], v[24:25] op_sel:[1,0,0]
	v_pk_fma_f32 v[10:11], v[110:111], v[42:43], v[10:11] op_sel:[1,0,0]
	v_pk_fma_f32 v[12:13], v[110:111], v[44:45], v[12:13] op_sel:[1,0,0]
	v_pk_fma_f32 v[14:15], v[110:111], v[46:47], v[14:15] op_sel:[1,0,0]
	v_pk_fma_f32 v[16:17], v[110:111], v[48:49], v[16:17] op_sel:[1,0,0]
	v_pk_fma_f32 v[18:19], v[110:111], v[50:51], v[18:19] op_sel:[1,0,0]
	v_pk_fma_f32 v[20:21], v[110:111], v[52:53], v[20:21] op_sel:[1,0,0]
	v_pk_fma_f32 v[22:23], v[110:111], v[54:55], v[22:23] op_sel:[1,0,0]
	v_pk_fma_f32 v[24:25], v[110:111], v[56:57], v[24:25] op_sel:[1,0,0]
	s_waitcnt vmcnt(16)
	v_cvt_pk_f32_fp8_e32 v[26:27], v168
	v_cvt_pk_f32_fp8_sdwa v[28:29], v168 src0_sel:WORD_1
	v_cvt_pk_f32_fp8_e32 v[30:31], v169
	v_cvt_pk_f32_fp8_sdwa v[32:33], v169 src0_sel:WORD_1
	v_cvt_pk_f32_fp8_e32 v[34:35], v170
	v_cvt_pk_f32_fp8_sdwa v[36:37], v170 src0_sel:WORD_1
	v_cvt_pk_f32_fp8_e32 v[38:39], v171
	v_cvt_pk_f32_fp8_sdwa v[40:41], v171 src0_sel:WORD_1
	v_cvt_pk_f32_fp8_e32 v[42:43], v172
	v_cvt_pk_f32_fp8_sdwa v[44:45], v172 src0_sel:WORD_1
	v_cvt_pk_f32_fp8_e32 v[46:47], v173
	v_cvt_pk_f32_fp8_sdwa v[48:49], v173 src0_sel:WORD_1
	v_cvt_pk_f32_fp8_e32 v[50:51], v174
	v_cvt_pk_f32_fp8_sdwa v[52:53], v174 src0_sel:WORD_1
	v_cvt_pk_f32_fp8_e32 v[54:55], v175
	v_cvt_pk_f32_fp8_sdwa v[56:57], v175 src0_sel:WORD_1
	global_load_dwordx4 v[168:171], v80, s[12:13]
	global_load_dwordx4 v[172:175], v81, s[12:13]
	v_pk_fma_f32 v[10:11], v[112:113], v[26:27], v[10:11] op_sel:[1,0,0]
	v_pk_fma_f32 v[12:13], v[112:113], v[28:29], v[12:13] op_sel:[1,0,0]
	v_pk_fma_f32 v[14:15], v[112:113], v[30:31], v[14:15] op_sel:[1,0,0]
	v_pk_fma_f32 v[16:17], v[112:113], v[32:33], v[16:17] op_sel:[1,0,0]
	v_pk_fma_f32 v[18:19], v[112:113], v[34:35], v[18:19] op_sel:[1,0,0]
	v_pk_fma_f32 v[20:21], v[112:113], v[36:37], v[20:21] op_sel:[1,0,0]
	v_pk_fma_f32 v[22:23], v[112:113], v[38:39], v[22:23] op_sel:[1,0,0]
	v_pk_fma_f32 v[24:25], v[112:113], v[40:41], v[24:25] op_sel:[1,0,0]
	v_pk_fma_f32 v[10:11], v[114:115], v[42:43], v[10:11] op_sel:[1,0,0]
	v_pk_fma_f32 v[12:13], v[114:115], v[44:45], v[12:13] op_sel:[1,0,0]
	v_pk_fma_f32 v[14:15], v[114:115], v[46:47], v[14:15] op_sel:[1,0,0]
	v_pk_fma_f32 v[16:17], v[114:115], v[48:49], v[16:17] op_sel:[1,0,0]
	v_pk_fma_f32 v[18:19], v[114:115], v[50:51], v[18:19] op_sel:[1,0,0]
	v_pk_fma_f32 v[20:21], v[114:115], v[52:53], v[20:21] op_sel:[1,0,0]
	v_pk_fma_f32 v[22:23], v[114:115], v[54:55], v[22:23] op_sel:[1,0,0]
	v_pk_fma_f32 v[24:25], v[114:115], v[56:57], v[24:25] op_sel:[1,0,0]
	s_waitcnt vmcnt(16)
;     DEVI float* wsmall() const { return (float*)(ws + WS_WSMALL); }
; #define LAS __attribute__((address_space(3)))
;     ...
;     for (int j0 = 0; j0 < NTL * 16; j0 += 16) {
;         u32x4_t w[16]; float cj[16];
; #pragma unroll
;         for (int jj = 0; jj < 16; ++jj) { const u32x2_t pr = pl[j0 + jj]; const int ej = __builtin_amdgcn_readfirstlane((int)pr.x); cj[jj] = __uint_as_float(pr.y);
;             w[jj] = *(const u32x4_t*)(v8 + (size_t)ej * D + 16 * lane); }
; #pragma unroll
;         for (int jj = 0; jj < 16; ++jj) { const float c = cj[jj];
; #pragma unroll
;             for (int q = 0; q < 4; ++q) { const f32x2_t lo = __builtin_amdgcn_cvt_pk_f32_fp8((int)w[jj][q], false), hi = __builtin_amdgcn_cvt_pk_f32_fp8((int)w[jj][q], true);
;                 o[4 * q] += c * lo[0]; o[4 * q + 1] += c * lo[1]; o[4 * q + 2] += c * hi[0]; o[4 * q + 3] += c * hi[1]; } }
;     }
;     if (NTL < 8) {
;         if (half == 1) {
; #pragma unroll
;             for (int q = 0; q < 4; ++q) *(LAS f32x4_t*)(xch + lane * 16 + 4 * q) = (f32x4_t){o[4 * q], o[4 * q + 1], o[4 * q + 2], o[4 * q + 3]};
;         }
;         __syncthreads();
;         if (half == 1) return;
; #pragma unroll
;         for (int q = 0; q < 4; ++q) { const f32x4_t t4 = *(const LAS f32x4_t*)(xch + lane * 16 + 4 * q); o[4 * q] += t4[0]; o[4 * q + 1] += t4[1]; o[4 * q + 2] += t4[2]; o[4 * q + 3] += t4[3]; }
;     }
;     const float* gp = gate2 + (size_t)row_seq(r) * 6144 + 16 * lane;
;     float* xp = x + (size_t)r * D + 16 * lane;
; #pragma unroll
;     for (int q = 0; q < 4; ++q) {
;         float4 xa = *(const float4*)(xp + 4 * q); const float4 ga = *(const float4*)(gp + 4 * q);
;         xa.x += ga.x * o[4 * q]; xa.y += ga.y * o[4 * q + 1]; xa.z += ga.z * o[4 * q + 2]; xa.w += ga.w * o[4 * q + 3];
;         *(float4*)(xp + 4 * q) = xa;
; template <int WHICH> DEVI void adaln_apply(const P& p, int l, int r, int lane_in, float (&v)[16]) {
;     ...
;         const float* ws = p.wsmall() + (size_t)l * 12 * D + 16 * lane;
	v_cvt_pk_f32_fp8_e32 v[26:27], v188
	v_cvt_pk_f32_fp8_sdwa v[28:29], v188 src0_sel:WORD_1
	v_cvt_pk_f32_fp8_e32 v[30:31], v189
	v_cvt_pk_f32_fp8_sdwa v[32:33], v189 src0_sel:WORD_1
	v_cvt_pk_f32_fp8_e32 v[34:35], v190
	v_cvt_pk_f32_fp8_sdwa v[36:37], v190 src0_sel:WORD_1
	v_cvt_pk_f32_fp8_e32 v[38:39], v191
	v_cvt_pk_f32_fp8_sdwa v[40:41], v191 src0_sel:WORD_1
	v_cvt_pk_f32_fp8_e32 v[42:43], v192
	v_cvt_pk_f32_fp8_sdwa v[44:45], v192 src0_sel:WORD_1
	v_cvt_pk_f32_fp8_e32 v[46:47], v193
	v_cvt_pk_f32_fp8_sdwa v[48:49], v193 src0_sel:WORD_1
	v_cvt_pk_f32_fp8_e32 v[50:51], v194
	v_cvt_pk_f32_fp8_sdwa v[52:53], v194 src0_sel:WORD_1
	v_cvt_pk_f32_fp8_e32 v[54:55], v195
	v_cvt_pk_f32_fp8_sdwa v[56:57], v195 src0_sel:WORD_1
	global_load_dwordx4 v[188:191], v82, s[12:13]
	global_load_dwordx4 v[192:195], v83, s[12:13]
	v_pk_fma_f32 v[10:11], v[180:181], v[26:27], v[10:11] op_sel:[1,0,0]
	v_pk_fma_f32 v[12:13], v[180:181], v[28:29], v[12:13] op_sel:[1,0,0]
	v_pk_fma_f32 v[14:15], v[180:181], v[30:31], v[14:15] op_sel:[1,0,0]
	v_pk_fma_f32 v[16:17], v[180:181], v[32:33], v[16:17] op_sel:[1,0,0]
	v_pk_fma_f32 v[18:19], v[180:181], v[34:35], v[18:19] op_sel:[1,0,0]
	v_pk_fma_f32 v[20:21], v[180:181], v[36:37], v[20:21] op_sel:[1,0,0]
	v_pk_fma_f32 v[22:23], v[180:181], v[38:39], v[22:23] op_sel:[1,0,0]
	v_pk_fma_f32 v[24:25], v[180:181], v[40:41], v[24:25] op_sel:[1,0,0]
	v_pk_fma_f32 v[10:11], v[182:183], v[42:43], v[10:11] op_sel:[1,0,0]
	v_pk_fma_f32 v[12:13], v[182:183], v[44:45], v[12:13] op_sel:[1,0,0]
	v_pk_fma_f32 v[14:15], v[182:183], v[46:47], v[14:15] op_sel:[1,0,0]
	v_pk_fma_f32 v[16:17], v[182:183], v[48:49], v[16:17] op_sel:[1,0,0]
	v_pk_fma_f32 v[18:19], v[182:183], v[50:51], v[18:19] op_sel:[1,0,0]
	v_pk_fma_f32 v[20:21], v[182:183], v[52:53], v[20:21] op_sel:[1,0,0]
	v_pk_fma_f32 v[22:23], v[182:183], v[54:55], v[22:23] op_sel:[1,0,0]
	v_pk_fma_f32 v[24:25], v[182:183], v[56:57], v[24:25] op_sel:[1,0,0]
	s_nop 1
	v_permlane32_swap_b32_e32 v10, v18
	v_permlane32_swap_b32_e32 v11, v19
	v_permlane32_swap_b32_e32 v12, v20
	v_permlane32_swap_b32_e32 v13, v21
	v_permlane32_swap_b32_e32 v14, v22
	v_permlane32_swap_b32_e32 v15, v23
	v_permlane32_swap_b32_e32 v16, v24
	v_permlane32_swap_b32_e32 v17, v25
	v_add_f32_e32 v10, v10, v18
	v_add_f32_e32 v11, v11, v19
	v_add_f32_e32 v12, v12, v20
	v_add_f32_e32 v13, v13, v21
	v_add_f32_e32 v14, v14, v22
	v_add_f32_e32 v15, v15, v23
	v_add_f32_e32 v16, v16, v24
	v_add_f32_e32 v17, v17, v25
	s_nop 1
	v_permlane16_swap_b32_e32 v10, v14
	v_permlane16_swap_b32_e32 v11, v15
	v_permlane16_swap_b32_e32 v12, v16
	v_permlane16_swap_b32_e32 v13, v17
	v_add_f32_e32 v10, v10, v14
	v_add_f32_e32 v11, v11, v15
	v_add_f32_e32 v12, v12, v16
	v_add_f32_e32 v13, v13, v17
	v_cndmask_b32_e64 v14, v10, v12, s[24:25]
	v_cndmask_b32_e64 v16, v12, v10, s[24:25]
	v_cndmask_b32_e64 v15, v11, v13, s[24:25]
	v_cndmask_b32_e64 v17, v13, v11, s[24:25]
	s_nop 1
	v_add_f32_dpp v62, v16, v14 row_ror:8 row_mask:0xf bank_mask:0xf
	v_add_f32_dpp v63, v17, v15 row_ror:8 row_mask:0xf bank_mask:0xf
	s_waitcnt vmcnt(16)
	v_pk_fma_f32 v[58:59], v[62:63], v[60:61], v[58:59]
	global_store_dwordx2 v6, v[58:59], s[14:15]
	s_add_u32 s22, s22, 1
	s_cmp_lg_u32 s22, 64
	s_cbranch_scc1 .Lg2_loop
	s_waitcnt vmcnt(0)
	v_cmp_gt_u32_e32 vcc, 8, v116
	s_nop 1
	s_add_u32 s9, s8, 1
	s_mul_i32 s9, s9, 0xc000
	s_add_u32 s10, s6, 0x1f812100
	s_addc_u32 s11, s7, 0
	s_add_u32 s10, s10, s9
	s_addc_u32 s11, s11, 0
	s_lshr_b32 s12, s85, 13
	s_mul_i32 s12, s12, 0x1800
	v_lshlrev_b32_e32 v2, 4, v1
	v_add_u32_e32 v2, s12, v2
	v_add_u32_e32 v4, 0x1000, v2
	global_load_dwordx4 v[132:135], v2, s[10:11] offset:0
	global_load_dwordx4 v[136:139], v2, s[10:11] offset:1024
	global_load_dwordx4 v[140:143], v2, s[10:11] offset:2048
	global_load_dwordx4 v[144:147], v2, s[10:11] offset:3072
	global_load_dwordx4 v[148:151], v4, s[10:11] offset:0
	global_load_dwordx4 v[152:155], v4, s[10:11] offset:1024
	v_add_u32_e32 v3, 0x14100, v2
	s_waitcnt vmcnt(0)
	ds_write_b128 v3, v[132:135] offset:0
	ds_write_b128 v3, v[136:139] offset:1024
	ds_write_b128 v3, v[140:143] offset:2048
	ds_write_b128 v3, v[144:147] offset:3072
	ds_write_b128 v3, v[148:151] offset:4096
	ds_write_b128 v3, v[152:155] offset:5120
	s_waitcnt lgkmcnt(0)
	s_barrier
	s_ashr_i32 s9, s8, 31
	s_lshl_b64 s[18:19], s[8:9], 24
	s_lshl_b64 s[10:11], s[8:9], 16
	s_add_u32 s9, s6, s10
	s_addc_u32 s13, s7, s11
	s_add_u32 s10, s9, 0x2fa42100
	s_addc_u32 s11, s13, 0
	s_add_u32 s12, s9, 0x2fa82100
	s_addc_u32 s13, s13, 0
	s_add_u32 s14, s6, 0x1b292100
	s_addc_u32 s15, s7, 0
	s_add_u32 s16, s6, 0x1bb12100
	s_addc_u32 s17, s7, 0
	s_add_u32 s18, s6, s18
	s_addc_u32 s19, s7, s19
	v_lshl_add_u64 v[2:3], s[18:19], 0, v[102:103]
	s_mov_b64 s[20:21], 0x1fa42100
	v_lshl_add_u64 v[104:105], v[2:3], 0, s[20:21]
	v_mov_b32_e32 v2, 0x1100000
	v_cndmask_b32_e64 v66, v2, 0, vcc
	v_lshl_add_u64 v[2:3], s[6:7], 0, v[66:67]
	s_add_u32 s49, s6, 0x4000
	v_lshl_add_u64 v[2:3], v[2:3], 0, v[102:103]
	s_mov_b64 s[20:21], 0x2fac2100
	s_addc_u32 s50, s7, 0
	v_lshl_add_u64 v[106:107], v[2:3], 0, s[20:21]
	s_add_u32 s20, s49, s47
	v_lshl_add_u64 v[2:3], s[18:19], 0, v[100:101]
	s_mov_b64 s[18:19], 0x27a42100
	s_addc_u32 s21, s50, s46
	v_lshl_add_u64 v[108:109], v[2:3], 0, s[18:19]
	v_lshlrev_b64 v[2:3], 2, v[100:101]
	v_lshl_add_u64 v[4:5], s[20:21], 0, v[2:3]
	s_mov_b64 s[18:19], 0x5000
	s_cmp_lt_i32 s8, 3
	v_lshl_add_u64 v[110:111], v[4:5], 0, s[18:19]
	s_cselect_b64 s[18:19], -1, 0
	s_add_i32 s24, s8, 1
	s_ashr_i32 s25, s24, 31
	s_lshl_b64 s[20:21], s[24:25], 12
	s_add_u32 s55, s6, 0x20e100
	s_addc_u32 s56, s7, 0
	s_lshl_b32 s26, s24, 2
	s_ashr_i32 s27, s26, 31
	s_mul_i32 s23, s24, 0xc000
	s_mul_hi_i32 s22, s24, 0xc000
	s_add_u32 s23, s6, s23
	s_addc_u32 s28, s7, s22
	s_add_u32 s22, s23, 0x1f812100
	s_addc_u32 s23, s28, 0
	s_add_u32 s57, s6, 0xcb8a100
	s_addc_u32 s58, s7, 0
	s_lshl_b64 s[28:29], s[24:25], 18
	s_add_u32 s59, s4, s28
	s_addc_u32 s60, s5, s29
	s_lshl_b32 s28, s24, 3
	s_ashr_i32 s29, s28, 31
	s_add_u32 s61, s6, 0xacda100
	s_mov_b32 s9, 0
	v_lshl_add_u64 v[112:113], s[4:5], 0, v[2:3]
	s_mul_hi_i32 s51, s24, 18
	s_mul_i32 s54, s24, 18
	s_addc_u32 s62, s7, 0
	s_lshl_b64 s[24:25], s[26:27], 2
	s_lshl_b64 s[26:27], s[28:29], 2
	s_mov_b32 s63, s48
	s_branch .LBB0_1087

;     DEVI float* mod() const { return (float*)(ws + WS_MOD); }
;     DEVI float* rstd() const { return (float*)(ws + WS_RSTD); }
;     ...
;     const float* gp = gate2 + (size_t)row_seq(r) * 6144 + 16 * lane;
;     float* xp = x + (size_t)r * D + 16 * lane;
; #pragma unroll
;     for (int q = 0; q < 4; ++q) {
;         float4 xa = *(const float4*)(xp + 4 * q); const float4 ga = *(const float4*)(gp + 4 * q);
;         xa.x += ga.x * o[4 * q]; xa.y += ga.y * o[4 * q + 1]; xa.z += ga.z * o[4 * q + 2]; xa.w += ga.w * o[4 * q + 3];
;         *(float4*)(xp + 4 * q) = xa;
;         o[4 * q] = xa.x; o[4 * q + 1] = xa.y; o[4 * q + 2] = xa.z; o[4 * q + 3] = xa.w;
;     }
; template <int WHICH> DEVI void adaln_apply(const P& p, int l, int r, int lane_in, float (&v)[16]) {
;     ...
;     float ss = 0.f;
; #pragma unroll
;     for (int i = 0; i < 16; ++i) ss += v[i] * v[i];
;     const float rstd = rsqrtf(wave_sum(ss) * (1.f / D) + EPS);
;     const float* md = p.mod() + ((size_t)l * NSEQ + row_seq(r)) * 6144 + 16 * lane;
; #pragma unroll
;     for (int q = 0; q < 4; ++q) {
;         const float4 gg = *(const float4*)(g + 4 * q), sc = *(const float4*)(md + osc + 4 * q), sh = *(const float4*)(md + osh + 4 * q);
.LBB0_1111:
	s_add_i32 s28, s64, s9
	s_mul_i32 s28, s28, s34
	s_add_i32 s28, s28, s48
	s_cmpk_gt_i32 s28, 0x3fff
	s_cbranch_scc1 .LBB0_1110
	v_mov_b32_e32 v114, 0
	s_mov_b32 s29, -16
	s_mov_b32 s30, s65
	v_mov_b32_e32 v115, v114
	v_mov_b32_e32 v120, v114
	v_mov_b32_e32 v121, v114
	v_mov_b32_e32 v118, v114
	v_mov_b32_e32 v119, v114
	v_mov_b32_e32 v128, v114
	v_mov_b32_e32 v129, v114
	v_mov_b32_e32 v130, v114
	v_mov_b32_e32 v131, v114
	v_mov_b32_e32 v122, v114
	v_mov_b32_e32 v123, v114
	v_mov_b32_e32 v124, v114
	v_mov_b32_e32 v125, v114
	v_mov_b32_e32 v126, v114
	v_mov_b32_e32 v127, v114
	s_ashr_i32 s29, s28, 31
	s_lshr_b32 s30, s29, 19
	s_add_i32 s30, s28, s30
	s_ashr_i32 s30, s30, 13
	v_mad_i64_i32 v[14:15], s[40:41], s30, v231, v[110:111]
	s_lshl_b64 s[40:41], s[28:29], 12
	s_nop 0
	v_lshl_add_u64 v[16:17], v[112:113], 0, s[40:41]
	global_load_dwordx4 v[2:5], v[14:15], off
	global_load_dwordx4 v[6:9], v[16:17], off sc1
	global_load_dwordx4 v[10:13], v[16:17], off offset:16 sc1
	s_waitcnt vmcnt(1)
	v_pk_fma_f32 v[30:31], v[120:121], v[2:3], v[6:7]
	v_pk_fma_f32 v[32:33], v[118:119], v[4:5], v[8:9]
	global_load_dwordx4 v[2:5], v[14:15], off offset:16
	s_waitcnt vmcnt(0)
	v_pk_fma_f32 v[22:23], v[128:129], v[2:3], v[10:11]
	v_pk_fma_f32 v[24:25], v[130:131], v[4:5], v[12:13]
	global_load_dwordx4 v[2:5], v[14:15], off offset:32
	global_load_dwordx4 v[6:9], v[16:17], off offset:32 sc1
	global_load_dwordx4 v[10:13], v[16:17], off offset:48 sc1
	s_waitcnt vmcnt(1)
	v_pk_fma_f32 v[26:27], v[122:123], v[2:3], v[6:7]
	v_pk_fma_f32 v[28:29], v[124:125], v[4:5], v[8:9]
	global_load_dwordx4 v[2:5], v[14:15], off offset:48
	s_waitcnt vmcnt(0)
	v_pk_fma_f32 v[18:19], v[126:127], v[2:3], v[10:11]
	v_pk_fma_f32 v[20:21], v[114:115], v[4:5], v[12:13]
	s_and_b64 vcc, exec, s[18:19]
	s_cbranch_vccz .LBB0_1110
	v_pk_mul_f32 v[2:3], v[30:31], v[30:31]
	v_pk_mul_f32 v[4:5], v[32:33], v[32:33]
	v_add_f32_e32 v2, v2, v3
	v_add_f32_e32 v2, v4, v2
	v_pk_mul_f32 v[6:7], v[22:23], v[22:23]
	v_add_f32_e32 v2, v5, v2
	v_add_f32_e32 v2, v2, v6
	v_pk_mul_f32 v[8:9], v[24:25], v[24:25]
	v_add_f32_e32 v2, v7, v2
	v_add_f32_e32 v2, v8, v2
	v_pk_mul_f32 v[10:11], v[26:27], v[26:27]
	v_add_f32_e32 v2, v9, v2
	v_add_f32_e32 v2, v2, v10
	v_pk_mul_f32 v[12:13], v[28:29], v[28:29]
	v_add_f32_e32 v2, v11, v2
	v_add_f32_e32 v2, v12, v2
	v_pk_mul_f32 v[14:15], v[18:19], v[18:19]
	v_add_f32_e32 v2, v13, v2
	v_add_f32_e32 v2, v2, v14
	v_pk_mul_f32 v[16:17], v[20:21], v[20:21]
	v_add_f32_e32 v2, v15, v2
	v_add_f32_e32 v2, v16, v2
	v_add_f32_e32 v4, v17, v2
	ds_bpermute_b32 v5, v179, v4
	v_mov_b32_e32 v58, v1
	s_load_dwordx2 s[40:41], s[0:1], 0x48
	s_ashr_i32 s31, s30, 31
	s_waitcnt lgkmcnt(0)
	v_add_f32_e32 v4, v4, v5
	ds_bpermute_b32 v5, v204, v4
	v_lshlrev_b32_e32 v60, 4, v58
	v_ashrrev_i32_e32 v61, 31, v60
	s_add_u32 s40, s40, s20
	s_addc_u32 s41, s41, s21
	s_waitcnt lgkmcnt(0)
	v_add_f32_e32 v4, v4, v5
	ds_bpermute_b32 v5, v205, v4
	v_lshlrev_b64 v[62:63], 2, v[60:61]
	v_lshl_add_u64 v[2:3], s[40:41], 0, v[62:63]
	s_mov_b32 s40, 0x800000
	s_add_u32 s30, s54, s30
	s_waitcnt lgkmcnt(0)
	v_add_f32_e32 v4, v4, v5
	ds_bpermute_b32 v5, v206, v4
	s_addc_u32 s31, s51, s31
	s_mulk_i32 s31, 0x6000
	s_mov_b64 s[42:43], 0x1000
	global_load_dwordx4 v[34:37], v[2:3], off offset:48
	global_load_dwordx4 v[38:41], v[2:3], off offset:32
	global_load_dwordx4 v[50:53], v[2:3], off offset:16
	global_load_dwordx4 v[68:71], v[2:3], off
	s_waitcnt lgkmcnt(0)
	v_add_f32_e32 v4, v4, v5
	ds_bpermute_b32 v5, v207, v4
	s_waitcnt lgkmcnt(0)
	v_add_f32_e32 v4, v4, v5
	ds_bpermute_b32 v5, v208, v4
	s_waitcnt lgkmcnt(0)
	v_add_f32_e32 v4, v4, v5
	v_fmamk_f32 v4, v4, 0x3a800000, v211
	v_cmp_gt_f32_e32 vcc, s40, v4
	v_mul_f32_e32 v5, 0x4b800000, v4
	s_mul_hi_u32 s40, s30, 0x6000
	v_cndmask_b32_e32 v4, v4, v5, vcc
	v_rsq_f32_e32 v4, v4
	s_add_i32 s40, s40, s31
	s_mulk_i32 s30, 0x6000
	s_add_u32 s30, s49, s30
	s_addc_u32 s31, s50, s40
	v_mul_f32_e32 v5, 0x45800000, v4
	v_lshl_add_u64 v[14:15], s[30:31], 0, v[62:63]
	s_movk_i32 s30, 0x1000
	v_cndmask_b32_e32 v59, v4, v5, vcc
	v_add_co_u32_e32 v2, vcc, s30, v14
	v_lshl_add_u64 v[4:5], v[14:15], 0, s[42:43]
	s_nop 0
	v_addc_co_u32_e32 v3, vcc, 0, v15, vcc
	global_load_dwordx4 v[72:75], v[2:3], off
	global_load_dwordx4 v[42:45], v[4:5], off offset:48
	global_load_dwordx4 v[46:49], v[4:5], off offset:32
	global_load_dwordx4 v[54:57], v[4:5], off offset:16
	s_nop 0
	global_load_dwordx4 v[2:5], v[14:15], off offset:48
	global_load_dwordx4 v[6:9], v[14:15], off offset:32
	global_load_dwordx4 v[10:13], v[14:15], off offset:16
	s_nop 0
	global_load_dwordx4 v[14:17], v[14:15], off
	v_mul_f32_e32 v30, v30, v59
	v_mul_f32_e32 v22, v22, v59
	s_lshl_b64 s[30:31], s[28:29], 11
	s_add_u32 s30, s55, s30
	s_addc_u32 s31, s56, s31
	s_waitcnt vmcnt(9)
	v_mul_f32_e32 v22, v22, v50
	s_waitcnt vmcnt(8)
	v_mul_f32_e32 v30, v68, v30
	s_waitcnt vmcnt(7)
	v_add_f32_e32 v64, 1.0, v72
	s_waitcnt vmcnt(0)
;     DEVI float* rstd() const { return (float*)(ws + WS_RSTD); }
;     DEVI bf16_t* hb() const { return (bf16_t*)(ws + WS_HB); }
;     DEVI float* wsmall() const { return (float*)(ws + WS_WSMALL); }
; DEVI unsigned pk2bf(float lo, float hi) { unsigned r; asm volatile("v_cvt_pk_bf16_f32 %0, %1, %2" : "=v"(r) : "v"(lo), "v"(hi)); return r; }
; template <int WHICH> DEVI void adaln_apply(const P& p, int l, int r, int lane_in, float (&v)[16]) {
;     ...
;         const float4 gg = *(const float4*)(g + 4 * q), sc = *(const float4*)(md + osc + 4 * q), sh = *(const float4*)(md + osh + 4 * q);
;         v[4 * q] = v[4 * q] * rstd * gg.x * (1.f + sc.x) + sh.x; v[4 * q + 1] = v[4 * q + 1] * rstd * gg.y * (1.f + sc.y) + sh.y;
;         v[4 * q + 2] = v[4 * q + 2] * rstd * gg.z * (1.f + sc.z) + sh.z; v[4 * q + 3] = v[4 * q + 3] * rstd * gg.w * (1.f + sc.w) + sh.w;
;     }
;     u32x4_t* ob = (u32x4_t*)(p.hb() + (size_t)r * D + 16 * lane);
;     ob[0] = (u32x4_t){pk2bf(v[0], v[1]), pk2bf(v[2], v[3]), pk2bf(v[4], v[5]), pk2bf(v[6], v[7])};
;     ob[1] = (u32x4_t){pk2bf(v[8], v[9]), pk2bf(v[10], v[11]), pk2bf(v[12], v[13]), pk2bf(v[14], v[15])};
;     ...
;         const float* ws = p.wsmall() + (size_t)l * 12 * D + 16 * lane;
;         float dot[12];
; #pragma unroll
;         for (int jj = 0; jj < 12; ++jj) { float a = 0.f;
; #pragma unroll
;             for (int q = 0; q < 4; ++q) { const float4 w = *(const float4*)(ws + (size_t)jj * D + 4 * q); a += v[4 * q] * w.x + v[4 * q + 1] * w.y + v[4 * q + 2] * w.z + v[4 * q + 3] * w.w; }
;             dot[jj] = wave_sum(a); }
	v_fma_f32 v14, v64, v30, v14
	v_mul_f32_e32 v30, v31, v59
	v_mul_f32_e32 v30, v69, v30
	v_add_f32_e32 v31, 1.0, v73
	v_fma_f32 v15, v31, v30, v15
	v_mul_f32_e32 v30, v32, v59
	v_mul_f32_e32 v30, v70, v30
	v_add_f32_e32 v31, 1.0, v74
	v_fma_f32 v16, v31, v30, v16
	v_mul_f32_e32 v30, v33, v59
	v_mul_f32_e32 v30, v71, v30
	v_add_f32_e32 v31, 1.0, v75
	v_fmac_f32_e32 v17, v31, v30
	v_add_f32_e32 v30, 1.0, v54
	v_fma_f32 v50, v22, v30, v10
	v_mul_f32_e32 v10, v23, v59
	v_mul_f32_e32 v10, v10, v51
	v_add_f32_e32 v22, 1.0, v55
	v_fma_f32 v51, v10, v22, v11
	v_mul_f32_e32 v10, v24, v59
	v_mul_f32_e32 v10, v10, v52
	v_add_f32_e32 v11, 1.0, v56
	v_fma_f32 v12, v10, v11, v12
	v_mul_f32_e32 v10, v25, v59
	v_mul_f32_e32 v10, v10, v53
	v_add_f32_e32 v11, 1.0, v57
	v_fmac_f32_e32 v13, v10, v11
	v_mul_f32_e32 v10, v26, v59
	v_mul_f32_e32 v10, v10, v38
	v_add_f32_e32 v11, 1.0, v46
	v_fma_f32 v38, v10, v11, v6
	v_mul_f32_e32 v6, v27, v59
	v_mul_f32_e32 v6, v6, v39
	v_add_f32_e32 v10, 1.0, v47
	v_fma_f32 v39, v6, v10, v7
	v_mul_f32_e32 v6, v28, v59
	v_mul_f32_e32 v6, v6, v40
	v_add_f32_e32 v7, 1.0, v48
	v_fma_f32 v40, v6, v7, v8
	v_mul_f32_e32 v6, v29, v59
	v_mul_f32_e32 v6, v6, v41
	v_add_f32_e32 v7, 1.0, v49
	v_fmac_f32_e32 v9, v6, v7
	v_mul_f32_e32 v6, v18, v59
	v_mul_f32_e32 v6, v6, v34
	v_add_f32_e32 v7, 1.0, v42
	v_fma_f32 v34, v6, v7, v2
	v_mul_f32_e32 v2, v19, v59
	v_mul_f32_e32 v2, v2, v35
	v_add_f32_e32 v6, 1.0, v43
	v_fma_f32 v35, v2, v6, v3
	v_mul_f32_e32 v2, v20, v59
	v_mul_f32_e32 v2, v2, v36
	v_add_f32_e32 v3, 1.0, v44
	v_fma_f32 v36, v2, v3, v4
	v_mul_f32_e32 v2, v21, v59
	v_mul_f32_e32 v2, v2, v37
	v_add_f32_e32 v3, 1.0, v45
	v_fmac_f32_e32 v5, v2, v3
	v_lshl_add_u64 v[2:3], v[60:61], 1, s[30:31]
	v_cvt_pk_bf16_f32 v18, v14, v15
	v_cvt_pk_bf16_f32 v19, v16, v17
	v_cvt_pk_bf16_f32 v20, v50, v51
	v_cvt_pk_bf16_f32 v21, v12, v13
	global_store_dwordx4 v[2:3], v[18:21], off
	s_nop 1
	v_cvt_pk_bf16_f32 v18, v38, v39
	v_cvt_pk_bf16_f32 v19, v40, v9
	v_cvt_pk_bf16_f32 v20, v34, v35
	v_cvt_pk_bf16_f32 v21, v36, v5
	global_store_dwordx4 v[2:3], v[18:21], off offset:16
	v_mov_b32_e32 v91, 0x14100
	v_lshl_add_u32 v90, v58, 6, v91
	v_mov_b32_e32 v88, 0
	v_mov_b32_e32 v89, 0
	ds_read_b128 v[132:135], v90 offset:0
	ds_read_b128 v[136:139], v90 offset:16
	ds_read_b128 v[140:143], v90 offset:32
	ds_read_b128 v[144:147], v90 offset:48
	ds_read_b128 v[148:151], v90 offset:4096
	ds_read_b128 v[152:155], v90 offset:4112
	ds_read_b128 v[156:159], v90 offset:4128
	ds_read_b128 v[160:163], v90 offset:4144
	ds_read_b128 v[164:167], v90 offset:8192
	ds_read_b128 v[168:171], v90 offset:8208
	ds_read_b128 v[172:175], v90 offset:8224
	ds_read_b128 v[180:183], v90 offset:8240
	ds_read_b128 v[184:187], v90 offset:12288
	ds_read_b128 v[188:191], v90 offset:12304
	ds_read_b128 v[192:195], v90 offset:12320
	ds_read_b128 v[196:199], v90 offset:12336
	s_waitcnt lgkmcnt(0)
	v_mul_f32_e32 v76, v14, v132
	v_mul_f32_e32 v77, v14, v148
	v_mul_f32_e32 v78, v14, v164
	v_mul_f32_e32 v79, v14, v184
	v_fmac_f32_e32 v76, v15, v133
	v_fmac_f32_e32 v77, v15, v149
	v_fmac_f32_e32 v78, v15, v165
	v_fmac_f32_e32 v79, v15, v185
	v_fmac_f32_e32 v76, v16, v134
	v_fmac_f32_e32 v77, v16, v150
	v_fmac_f32_e32 v78, v16, v166
	v_fmac_f32_e32 v79, v16, v186
	v_fmac_f32_e32 v76, v17, v135
	v_fmac_f32_e32 v77, v17, v151
	v_fmac_f32_e32 v78, v17, v167
	v_fmac_f32_e32 v79, v17, v187
	v_fmac_f32_e32 v76, v50, v136
	v_fmac_f32_e32 v77, v50, v152
	v_fmac_f32_e32 v78, v50, v168
	v_fmac_f32_e32 v79, v50, v188
	v_fmac_f32_e32 v76, v51, v137
	v_fmac_f32_e32 v77, v51, v153
	v_fmac_f32_e32 v78, v51, v169
	v_fmac_f32_e32 v79, v51, v189
	v_fmac_f32_e32 v76, v12, v138
	v_fmac_f32_e32 v77, v12, v154
	v_fmac_f32_e32 v78, v12, v170
	v_fmac_f32_e32 v79, v12, v190
	v_fmac_f32_e32 v76, v13, v139
	v_fmac_f32_e32 v77, v13, v155
	v_fmac_f32_e32 v78, v13, v171
	v_fmac_f32_e32 v79, v13, v191
	v_fmac_f32_e32 v76, v38, v140
	v_fmac_f32_e32 v77, v38, v156
	v_fmac_f32_e32 v78, v38, v172
	v_fmac_f32_e32 v79, v38, v192
	v_fmac_f32_e32 v76, v39, v141
	v_fmac_f32_e32 v77, v39, v157
	v_fmac_f32_e32 v78, v39, v173
	v_fmac_f32_e32 v79, v39, v193
	v_fmac_f32_e32 v76, v40, v142
	v_fmac_f32_e32 v77, v40, v158
	v_fmac_f32_e32 v78, v40, v174
	v_fmac_f32_e32 v79, v40, v194
	v_fmac_f32_e32 v76, v9, v143
	v_fmac_f32_e32 v77, v9, v159
	v_fmac_f32_e32 v78, v9, v175
	v_fmac_f32_e32 v79, v9, v195
	v_fmac_f32_e32 v76, v34, v144
	v_fmac_f32_e32 v77, v34, v160
	v_fmac_f32_e32 v78, v34, v180
	v_fmac_f32_e32 v79, v34, v196
	v_fmac_f32_e32 v76, v35, v145
	v_fmac_f32_e32 v77, v35, v161
	v_fmac_f32_e32 v78, v35, v181
	v_fmac_f32_e32 v79, v35, v197
	v_fmac_f32_e32 v76, v36, v146
	v_fmac_f32_e32 v77, v36, v162
	v_fmac_f32_e32 v78, v36, v182
	v_fmac_f32_e32 v79, v36, v198
	v_fmac_f32_e32 v76, v5, v147
	v_fmac_f32_e32 v77, v5, v163
	v_fmac_f32_e32 v78, v5, v183
	v_fmac_f32_e32 v79, v5, v199
	ds_read_b128 v[132:135], v90 offset:16384
	ds_read_b128 v[136:139], v90 offset:16400
	ds_read_b128 v[140:143], v90 offset:16416
	ds_read_b128 v[144:147], v90 offset:16432
	ds_read_b128 v[148:151], v90 offset:20480
	ds_read_b128 v[152:155], v90 offset:20496
	ds_read_b128 v[156:159], v90 offset:20512
	ds_read_b128 v[160:163], v90 offset:20528
	ds_read_b128 v[164:167], v90 offset:24576
	ds_read_b128 v[168:171], v90 offset:24592
	ds_read_b128 v[172:175], v90 offset:24608
	ds_read_b128 v[180:183], v90 offset:24624
	ds_read_b128 v[184:187], v90 offset:28672
	ds_read_b128 v[188:191], v90 offset:28688
	ds_read_b128 v[192:195], v90 offset:28704
	ds_read_b128 v[196:199], v90 offset:28720
	s_waitcnt lgkmcnt(0)
; DEVI float wave_sum(float v) {
; #pragma unroll
;     for (int o = 1; o < 64; o <<= 1) v += __shfl_xor(v, o);
;     return v;
; template <int WHICH> DEVI void adaln_apply(const P& p, int l, int r, int lane_in, float (&v)[16]) {
;     ...
;         for (int jj = 0; jj < 12; ++jj) { float a = 0.f;
; #pragma unroll
;             for (int q = 0; q < 4; ++q) { const float4 w = *(const float4*)(ws + (size_t)jj * D + 4 * q); a += v[4 * q] * w.x + v[4 * q + 1] * w.y + v[4 * q + 2] * w.z + v[4 * q + 3] * w.w; }
;             dot[jj] = wave_sum(a); }
	v_mul_f32_e32 v80, v14, v132
	v_mul_f32_e32 v81, v14, v148
	v_mul_f32_e32 v82, v14, v164
	v_mul_f32_e32 v83, v14, v184
	v_fmac_f32_e32 v80, v15, v133
	v_fmac_f32_e32 v81, v15, v149
	v_fmac_f32_e32 v82, v15, v165
	v_fmac_f32_e32 v83, v15, v185
	v_fmac_f32_e32 v80, v16, v134
	v_fmac_f32_e32 v81, v16, v150
	v_fmac_f32_e32 v82, v16, v166
	v_fmac_f32_e32 v83, v16, v186
	v_fmac_f32_e32 v80, v17, v135
	v_fmac_f32_e32 v81, v17, v151
	v_fmac_f32_e32 v82, v17, v167
	v_fmac_f32_e32 v83, v17, v187
	v_fmac_f32_e32 v80, v50, v136
	v_fmac_f32_e32 v81, v50, v152
	v_fmac_f32_e32 v82, v50, v168
	v_fmac_f32_e32 v83, v50, v188
	v_fmac_f32_e32 v80, v51, v137
	v_fmac_f32_e32 v81, v51, v153
	v_fmac_f32_e32 v82, v51, v169
	v_fmac_f32_e32 v83, v51, v189
	v_fmac_f32_e32 v80, v12, v138
	v_fmac_f32_e32 v81, v12, v154
	v_fmac_f32_e32 v82, v12, v170
	v_fmac_f32_e32 v83, v12, v190
	v_fmac_f32_e32 v80, v13, v139
	v_fmac_f32_e32 v81, v13, v155
	v_fmac_f32_e32 v82, v13, v171
	v_fmac_f32_e32 v83, v13, v191
	v_fmac_f32_e32 v80, v38, v140
	v_fmac_f32_e32 v81, v38, v156
	v_fmac_f32_e32 v82, v38, v172
	v_fmac_f32_e32 v83, v38, v192
	v_fmac_f32_e32 v80, v39, v141
	v_fmac_f32_e32 v81, v39, v157
	v_fmac_f32_e32 v82, v39, v173
	v_fmac_f32_e32 v83, v39, v193
	v_fmac_f32_e32 v80, v40, v142
	v_fmac_f32_e32 v81, v40, v158
	v_fmac_f32_e32 v82, v40, v174
	v_fmac_f32_e32 v83, v40, v194
	v_fmac_f32_e32 v80, v9, v143
	v_fmac_f32_e32 v81, v9, v159
	v_fmac_f32_e32 v82, v9, v175
	v_fmac_f32_e32 v83, v9, v195
	v_fmac_f32_e32 v80, v34, v144
	v_fmac_f32_e32 v81, v34, v160
	v_fmac_f32_e32 v82, v34, v180
	v_fmac_f32_e32 v83, v34, v196
	v_fmac_f32_e32 v80, v35, v145
	v_fmac_f32_e32 v81, v35, v161
	v_fmac_f32_e32 v82, v35, v181
	v_fmac_f32_e32 v83, v35, v197
	v_fmac_f32_e32 v80, v36, v146
	v_fmac_f32_e32 v81, v36, v162
	v_fmac_f32_e32 v82, v36, v182
	v_fmac_f32_e32 v83, v36, v198
	v_fmac_f32_e32 v80, v5, v147
	v_fmac_f32_e32 v81, v5, v163
	v_fmac_f32_e32 v82, v5, v183
	v_fmac_f32_e32 v83, v5, v199
	ds_read_b128 v[132:135], v90 offset:32768
	ds_read_b128 v[136:139], v90 offset:32784
	ds_read_b128 v[140:143], v90 offset:32800
	ds_read_b128 v[144:147], v90 offset:32816
	ds_read_b128 v[148:151], v90 offset:36864
	ds_read_b128 v[152:155], v90 offset:36880
	ds_read_b128 v[156:159], v90 offset:36896
	ds_read_b128 v[160:163], v90 offset:36912
	ds_read_b128 v[164:167], v90 offset:40960
	ds_read_b128 v[168:171], v90 offset:40976
	ds_read_b128 v[172:175], v90 offset:40992
	ds_read_b128 v[180:183], v90 offset:41008
	ds_read_b128 v[184:187], v90 offset:45056
	ds_read_b128 v[188:191], v90 offset:45072
	ds_read_b128 v[192:195], v90 offset:45088
	ds_read_b128 v[196:199], v90 offset:45104
	s_waitcnt lgkmcnt(0)
	v_mul_f32_e32 v84, v14, v132
	v_mul_f32_e32 v85, v14, v148
	v_mul_f32_e32 v86, v14, v164
	v_mul_f32_e32 v87, v14, v184
	v_fmac_f32_e32 v84, v15, v133
	v_fmac_f32_e32 v85, v15, v149
	v_fmac_f32_e32 v86, v15, v165
	v_fmac_f32_e32 v87, v15, v185
	v_fmac_f32_e32 v84, v16, v134
	v_fmac_f32_e32 v85, v16, v150
	v_fmac_f32_e32 v86, v16, v166
	v_fmac_f32_e32 v87, v16, v186
	v_fmac_f32_e32 v84, v17, v135
	v_fmac_f32_e32 v85, v17, v151
	v_fmac_f32_e32 v86, v17, v167
	v_fmac_f32_e32 v87, v17, v187
	v_fmac_f32_e32 v84, v50, v136
	v_fmac_f32_e32 v85, v50, v152
	v_fmac_f32_e32 v86, v50, v168
	v_fmac_f32_e32 v87, v50, v188
	v_fmac_f32_e32 v84, v51, v137
	v_fmac_f32_e32 v85, v51, v153
	v_fmac_f32_e32 v86, v51, v169
	v_fmac_f32_e32 v87, v51, v189
	v_fmac_f32_e32 v84, v12, v138
	v_fmac_f32_e32 v85, v12, v154
	v_fmac_f32_e32 v86, v12, v170
	v_fmac_f32_e32 v87, v12, v190
	v_fmac_f32_e32 v84, v13, v139
	v_fmac_f32_e32 v85, v13, v155
	v_fmac_f32_e32 v86, v13, v171
	v_fmac_f32_e32 v87, v13, v191
	v_fmac_f32_e32 v84, v38, v140
	v_fmac_f32_e32 v85, v38, v156
	v_fmac_f32_e32 v86, v38, v172
	v_fmac_f32_e32 v87, v38, v192
	v_fmac_f32_e32 v84, v39, v141
	v_fmac_f32_e32 v85, v39, v157
	v_fmac_f32_e32 v86, v39, v173
	v_fmac_f32_e32 v87, v39, v193
	v_fmac_f32_e32 v84, v40, v142
	v_fmac_f32_e32 v85, v40, v158
	v_fmac_f32_e32 v86, v40, v174
	v_fmac_f32_e32 v87, v40, v194
	v_fmac_f32_e32 v84, v9, v143
	v_fmac_f32_e32 v85, v9, v159
	v_fmac_f32_e32 v86, v9, v175
	v_fmac_f32_e32 v87, v9, v195
	v_fmac_f32_e32 v84, v34, v144
	v_fmac_f32_e32 v85, v34, v160
	v_fmac_f32_e32 v86, v34, v180
	v_fmac_f32_e32 v87, v34, v196
	v_fmac_f32_e32 v84, v35, v145
	v_fmac_f32_e32 v85, v35, v161
	v_fmac_f32_e32 v86, v35, v181
	v_fmac_f32_e32 v87, v35, v197
	v_fmac_f32_e32 v84, v36, v146
	v_fmac_f32_e32 v85, v36, v162
	v_fmac_f32_e32 v86, v36, v182
	v_fmac_f32_e32 v87, v36, v198
	v_fmac_f32_e32 v84, v5, v147
	v_fmac_f32_e32 v85, v5, v163
	v_fmac_f32_e32 v86, v5, v183
	v_fmac_f32_e32 v87, v5, v199
	s_nop 1
	v_add_f32_dpp v76, v76, v76 quad_perm:[1,0,3,2] row_mask:0xf bank_mask:0xf
	v_add_f32_dpp v77, v77, v77 quad_perm:[1,0,3,2] row_mask:0xf bank_mask:0xf
	v_add_f32_dpp v78, v78, v78 quad_perm:[1,0,3,2] row_mask:0xf bank_mask:0xf
	v_add_f32_dpp v79, v79, v79 quad_perm:[1,0,3,2] row_mask:0xf bank_mask:0xf
	v_add_f32_dpp v80, v80, v80 quad_perm:[1,0,3,2] row_mask:0xf bank_mask:0xf
	v_add_f32_dpp v81, v81, v81 quad_perm:[1,0,3,2] row_mask:0xf bank_mask:0xf
	v_add_f32_dpp v82, v82, v82 quad_perm:[1,0,3,2] row_mask:0xf bank_mask:0xf
	v_add_f32_dpp v83, v83, v83 quad_perm:[1,0,3,2] row_mask:0xf bank_mask:0xf
	v_add_f32_dpp v84, v84, v84 quad_perm:[1,0,3,2] row_mask:0xf bank_mask:0xf
	v_add_f32_dpp v85, v85, v85 quad_perm:[1,0,3,2] row_mask:0xf bank_mask:0xf
	v_add_f32_dpp v86, v86, v86 quad_perm:[1,0,3,2] row_mask:0xf bank_mask:0xf
	v_add_f32_dpp v87, v87, v87 quad_perm:[1,0,3,2] row_mask:0xf bank_mask:0xf
	v_add_f32_dpp v76, v76, v76 quad_perm:[2,3,0,1] row_mask:0xf bank_mask:0xf
;     DEVI float* dt() const { return (float*)(ws + WS_DT); }
; DEVI float softplus_f(float x) { return x > 20.f ? x : log1pf(expf(x)); }
; DEVI float wave_sum(float v) {
; #pragma unroll
;     for (int o = 1; o < 64; o <<= 1) v += __shfl_xor(v, o);
;     return v;
; template <int WHICH> DEVI void adaln_apply(const P& p, int l, int r, int lane_in, float (&v)[16]) {
;     ...
;             dot[jj] = wave_sum(a); }
;         if (lane < 8) {
;             float d = dot[0];
; #pragma unroll
;             for (int jj = 1; jj < 8; ++jj) d = (lane == jj) ? dot[jj] : d;
;             p.dt()[(size_t)r * 8 + lane] = softplus_f(d + dtb[lane]);
;         } else if (lane < 12) {
;             const int hd = lane - 8; float d = dot[8];
; #pragma unroll
;             for (int jj = 9; jj < 12; ++jj) d = (lane == jj) ? dot[jj] : d;
;             const float lf = -softplus_f(-(d + fb[hd]));
	v_add_f32_dpp v77, v77, v77 quad_perm:[2,3,0,1] row_mask:0xf bank_mask:0xf
	v_add_f32_dpp v78, v78, v78 quad_perm:[2,3,0,1] row_mask:0xf bank_mask:0xf
	v_add_f32_dpp v79, v79, v79 quad_perm:[2,3,0,1] row_mask:0xf bank_mask:0xf
	v_add_f32_dpp v80, v80, v80 quad_perm:[2,3,0,1] row_mask:0xf bank_mask:0xf
	v_add_f32_dpp v81, v81, v81 quad_perm:[2,3,0,1] row_mask:0xf bank_mask:0xf
	v_add_f32_dpp v82, v82, v82 quad_perm:[2,3,0,1] row_mask:0xf bank_mask:0xf
	v_add_f32_dpp v83, v83, v83 quad_perm:[2,3,0,1] row_mask:0xf bank_mask:0xf
	v_add_f32_dpp v84, v84, v84 quad_perm:[2,3,0,1] row_mask:0xf bank_mask:0xf
	v_add_f32_dpp v85, v85, v85 quad_perm:[2,3,0,1] row_mask:0xf bank_mask:0xf
	v_add_f32_dpp v86, v86, v86 quad_perm:[2,3,0,1] row_mask:0xf bank_mask:0xf
	v_add_f32_dpp v87, v87, v87 quad_perm:[2,3,0,1] row_mask:0xf bank_mask:0xf
	v_add_f32_dpp v76, v76, v76 row_half_mirror row_mask:0xf bank_mask:0xf
	v_add_f32_dpp v77, v77, v77 row_half_mirror row_mask:0xf bank_mask:0xf
	v_add_f32_dpp v78, v78, v78 row_half_mirror row_mask:0xf bank_mask:0xf
	v_add_f32_dpp v79, v79, v79 row_half_mirror row_mask:0xf bank_mask:0xf
	v_add_f32_dpp v80, v80, v80 row_half_mirror row_mask:0xf bank_mask:0xf
	v_add_f32_dpp v81, v81, v81 row_half_mirror row_mask:0xf bank_mask:0xf
	v_add_f32_dpp v82, v82, v82 row_half_mirror row_mask:0xf bank_mask:0xf
	v_add_f32_dpp v83, v83, v83 row_half_mirror row_mask:0xf bank_mask:0xf
	v_add_f32_dpp v84, v84, v84 row_half_mirror row_mask:0xf bank_mask:0xf
	v_add_f32_dpp v85, v85, v85 row_half_mirror row_mask:0xf bank_mask:0xf
	v_add_f32_dpp v86, v86, v86 row_half_mirror row_mask:0xf bank_mask:0xf
	v_add_f32_dpp v87, v87, v87 row_half_mirror row_mask:0xf bank_mask:0xf
	v_add_f32_dpp v76, v76, v76 row_mirror row_mask:0xf bank_mask:0xf
	v_add_f32_dpp v77, v77, v77 row_mirror row_mask:0xf bank_mask:0xf
	v_add_f32_dpp v78, v78, v78 row_mirror row_mask:0xf bank_mask:0xf
	v_add_f32_dpp v79, v79, v79 row_mirror row_mask:0xf bank_mask:0xf
	v_add_f32_dpp v80, v80, v80 row_mirror row_mask:0xf bank_mask:0xf
	v_add_f32_dpp v81, v81, v81 row_mirror row_mask:0xf bank_mask:0xf
	v_add_f32_dpp v82, v82, v82 row_mirror row_mask:0xf bank_mask:0xf
	v_add_f32_dpp v83, v83, v83 row_mirror row_mask:0xf bank_mask:0xf
	v_add_f32_dpp v84, v84, v84 row_mirror row_mask:0xf bank_mask:0xf
	v_add_f32_dpp v85, v85, v85 row_mirror row_mask:0xf bank_mask:0xf
	v_add_f32_dpp v86, v86, v86 row_mirror row_mask:0xf bank_mask:0xf
	v_add_f32_dpp v87, v87, v87 row_mirror row_mask:0xf bank_mask:0xf
	v_add_f32_dpp v76, v76, v76 row_bcast:15 row_mask:0xa bank_mask:0xf
	v_add_f32_dpp v77, v77, v77 row_bcast:15 row_mask:0xa bank_mask:0xf
	v_add_f32_dpp v78, v78, v78 row_bcast:15 row_mask:0xa bank_mask:0xf
	v_add_f32_dpp v79, v79, v79 row_bcast:15 row_mask:0xa bank_mask:0xf
	v_add_f32_dpp v80, v80, v80 row_bcast:15 row_mask:0xa bank_mask:0xf
	v_add_f32_dpp v81, v81, v81 row_bcast:15 row_mask:0xa bank_mask:0xf
	v_add_f32_dpp v82, v82, v82 row_bcast:15 row_mask:0xa bank_mask:0xf
	v_add_f32_dpp v83, v83, v83 row_bcast:15 row_mask:0xa bank_mask:0xf
	v_add_f32_dpp v84, v84, v84 row_bcast:15 row_mask:0xa bank_mask:0xf
	v_add_f32_dpp v85, v85, v85 row_bcast:15 row_mask:0xa bank_mask:0xf
	v_add_f32_dpp v86, v86, v86 row_bcast:15 row_mask:0xa bank_mask:0xf
	v_add_f32_dpp v87, v87, v87 row_bcast:15 row_mask:0xa bank_mask:0xf
	v_add_f32_dpp v76, v76, v76 row_bcast:31 row_mask:0xc bank_mask:0xf
	v_add_f32_dpp v77, v77, v77 row_bcast:31 row_mask:0xc bank_mask:0xf
	v_add_f32_dpp v78, v78, v78 row_bcast:31 row_mask:0xc bank_mask:0xf
	v_add_f32_dpp v79, v79, v79 row_bcast:31 row_mask:0xc bank_mask:0xf
	v_add_f32_dpp v80, v80, v80 row_bcast:31 row_mask:0xc bank_mask:0xf
	v_add_f32_dpp v81, v81, v81 row_bcast:31 row_mask:0xc bank_mask:0xf
	v_add_f32_dpp v82, v82, v82 row_bcast:31 row_mask:0xc bank_mask:0xf
	v_add_f32_dpp v83, v83, v83 row_bcast:31 row_mask:0xc bank_mask:0xf
	v_add_f32_dpp v84, v84, v84 row_bcast:31 row_mask:0xc bank_mask:0xf
	v_add_f32_dpp v85, v85, v85 row_bcast:31 row_mask:0xc bank_mask:0xf
	v_add_f32_dpp v86, v86, v86 row_bcast:31 row_mask:0xc bank_mask:0xf
	v_add_f32_dpp v87, v87, v87 row_bcast:31 row_mask:0xc bank_mask:0xf
	s_nop 1
	v_readlane_b32 s30, v76, 63
	v_readlane_b32 s31, v77, 63
	v_readlane_b32 s40, v78, 63
	v_readlane_b32 s41, v79, 63
	v_readlane_b32 s42, v80, 63
	v_readlane_b32 s43, v81, 63
	s_nop 1
	v_writelane_b32 v88, s30, 0
	v_writelane_b32 v88, s31, 1
	v_writelane_b32 v88, s40, 2
	v_writelane_b32 v88, s41, 3
	v_writelane_b32 v88, s42, 4
	v_writelane_b32 v88, s43, 5
	v_readlane_b32 s30, v82, 63
	v_readlane_b32 s31, v83, 63
	v_readlane_b32 s40, v84, 63
	v_readlane_b32 s41, v85, 63
	v_readlane_b32 s42, v86, 63
	v_readlane_b32 s43, v87, 63
	s_nop 1
	v_writelane_b32 v88, s30, 6
	v_writelane_b32 v88, s31, 7
	v_writelane_b32 v88, s40, 8
	v_writelane_b32 v88, s41, 9
	v_writelane_b32 v88, s42, 10
	v_writelane_b32 v88, s43, 11
	v_mov_b32_e32 v4, v88
	v_mov_b32_e32 v37, v88
	v_mov_b32_e32 v42, v88
	v_mov_b32_e32 v44, v88
	v_mov_b32_e32 v46, v88
	v_mov_b32_e32 v48, v88
	v_mov_b32_e32 v52, v88
	v_mov_b32_e32 v54, v88
	v_mov_b32_e32 v56, v88
	v_mov_b32_e32 v6, v88
	v_mov_b32_e32 v10, v88
	v_mov_b32_e32 v2, v88
	v_mov_b32_e32 v8, v89
	v_mov_b32_e32 v41, v89
	v_mov_b32_e32 v43, v89
	v_mov_b32_e32 v45, v89
	v_mov_b32_e32 v47, v89
	v_mov_b32_e32 v49, v89
	v_mov_b32_e32 v53, v89
	v_mov_b32_e32 v55, v89
	v_mov_b32_e32 v57, v89
	v_mov_b32_e32 v7, v89
	v_mov_b32_e32 v11, v89
	v_mov_b32_e32 v3, v89
	s_load_dwordx2 s[30:31], s[0:1], 0x80
	s_load_dwordx2 s[40:41], s[0:1], 0xb0
	s_waitcnt lgkmcnt(0)
	v_cmp_lt_i32_e32 vcc, 7, v58
	s_nop 3
	s_and_saveexec_b64 s[42:43], vcc
	s_xor_b64 s[42:43], exec, s[42:43]
	s_cbranch_execz .LBB0_1121
;     DEVI float* logf() const { return (float*)(ws + WS_LOGF); }
; DEVI float softplus_f(float x) { return x > 20.f ? x : log1pf(expf(x)); }
; template <int WHICH> DEVI void adaln_apply(const P& p, int l, int r, int lane_in, float (&v)[16]) {
;     ...
;         } else if (lane < 12) {
;             const int hd = lane - 8; float d = dot[8];
; #pragma unroll
;             for (int jj = 9; jj < 12; ++jj) d = (lane == jj) ? dot[jj] : d;
;             const float lf = -softplus_f(-(d + fb[hd]));
;             p.logf()[(size_t)r * 4 + hd] = lf;
;             if (r < M_P) p.out[OUT_LFP + ((size_t)l * M_P + r) * 4 + hd] = lf; else p.out[OUT_LFS + ((size_t)l * M_S + (r - M_P)) * 4 + hd] = lf;
	v_cmp_gt_u32_e32 vcc, 12, v58
	s_and_saveexec_b64 s[44:45], vcc
	s_cbranch_execz .LBB0_1120
	s_add_u32 s40, s40, s24
	s_addc_u32 s41, s41, s25
	v_add_u32_e32 v66, -8, v58
	v_lshl_add_u64 v[4:5], v[66:67], 2, s[40:41]
	global_load_dword v4, v[4:5], off
	v_add_f32_e32 v5, v56, v57
	v_add_f32_e32 v6, v6, v7
	v_cmp_eq_u32_e32 vcc, 9, v58
	v_add_f32_e32 v7, v10, v11
	s_waitcnt lgkmcnt(0)
	v_add_f32_e32 v2, v2, v3
	v_cndmask_b32_e32 v3, v5, v6, vcc
	v_cmp_eq_u32_e32 vcc, 10, v58
	s_mov_b32 s40, 0xc1a00000
	s_nop 0
	v_cndmask_b32_e32 v3, v3, v7, vcc
	v_cmp_eq_u32_e32 vcc, 11, v58
	s_nop 1
	v_cndmask_b32_e32 v2, v3, v2, vcc
	s_waitcnt vmcnt(0)
	v_add_f32_e32 v2, v2, v4
	v_xor_b32_e32 v3, 0x80000000, v2
	v_cmp_ngt_f32_e32 vcc, s40, v2
	s_and_saveexec_b64 s[40:41], vcc
	s_cbranch_execz .LBB0_1119
	v_mul_f32_e32 v3, 0xbfb8aa3b, v2
	v_rndne_f32_e32 v4, v3
	s_mov_b32 s66, 0xbfb8aa3b
	v_sub_f32_e32 v5, v3, v4
	v_fma_f32 v3, v2, s66, -v3
	v_fmac_f32_e32 v3, 0xb2a5705f, v2
	v_add_f32_e32 v3, v5, v3
	v_cvt_i32_f32_e32 v4, v4
	v_exp_f32_e32 v3, v3
	s_mov_b32 s66, 0x42ce8ed0
	v_cmp_nlt_f32_e32 vcc, s66, v2
	s_mov_b32 s66, 0xc2b17218
	v_ldexp_f32 v3, v3, v4
	v_cndmask_b32_e32 v3, 0, v3, vcc
	v_cmp_ngt_f32_e32 vcc, s66, v2
	s_mov_b32 s66, 0x3f2aaaab
	s_nop 0
	v_cndmask_b32_e32 v16, v215, v3, vcc
	v_add_f32_e32 v4, 1.0, v16
	v_add_f32_e32 v2, -1.0, v4
	v_sub_f32_e32 v3, v2, v4
	v_add_f32_e32 v3, 1.0, v3
	v_sub_f32_e32 v2, v16, v2
	v_add_f32_e32 v5, v2, v3
	v_frexp_mant_f32_e32 v6, v4
	v_cvt_f64_f32_e32 v[2:3], v4
	v_frexp_exp_i32_f64_e32 v2, v[2:3]
	v_cmp_gt_f32_e32 vcc, s66, v6
	s_mov_b32 s66, 0x3f317218
	s_nop 0
	v_subbrev_co_u32_e32 v10, vcc, 0, v2, vcc
	v_sub_u32_e32 v2, 0, v10
	v_ldexp_f32 v3, v4, v2
	v_add_f32_e32 v4, -1.0, v3
	v_add_f32_e32 v6, 1.0, v3
	v_ldexp_f32 v2, v5, v2
	v_add_f32_e32 v5, 1.0, v4
	v_add_f32_e32 v7, -1.0, v6
	v_sub_f32_e32 v5, v3, v5
	v_sub_f32_e32 v3, v3, v7
	v_add_f32_e32 v5, v2, v5
	v_add_f32_e32 v2, v2, v3
	v_add_f32_e32 v11, v6, v2
	v_rcp_f32_e32 v13, v11
	v_sub_f32_e32 v3, v6, v11
	v_add_f32_e32 v12, v2, v3
	v_add_f32_e32 v3, v4, v5
	v_mul_f32_e32 v15, v3, v13
	v_sub_f32_e32 v2, v4, v3
	v_mul_f32_e32 v4, v11, v15
	v_fma_f32 v6, v15, v11, -v4
	v_fmac_f32_e32 v6, v15, v12
	v_add_f32_e32 v14, v5, v2
	v_add_f32_e32 v2, v4, v6
	v_sub_f32_e32 v5, v3, v2
	v_pk_add_f32 v[8:9], v[2:3], v[4:5] neg_lo:[0,1] neg_hi:[0,1]
	v_mov_b32_e32 v7, v2
	v_pk_add_f32 v[2:3], v[8:9], v[6:7] neg_lo:[0,1] neg_hi:[0,1]
	s_nop 0
	v_add_f32_e32 v3, v14, v3
	v_add_f32_e32 v2, v2, v3
	v_add_f32_e32 v3, v5, v2
	v_mul_f32_e32 v14, v13, v3
	v_mul_f32_e32 v4, v11, v14
	v_fma_f32 v6, v14, v11, -v4
	v_fmac_f32_e32 v6, v14, v12
	v_sub_f32_e32 v5, v5, v3
	v_add_f32_e32 v11, v2, v5
	v_add_f32_e32 v2, v4, v6
	v_sub_f32_e32 v5, v3, v2
	v_pk_add_f32 v[8:9], v[2:3], v[4:5] neg_lo:[0,1] neg_hi:[0,1]
	v_mov_b32_e32 v7, v2
	v_pk_add_f32 v[2:3], v[8:9], v[6:7] neg_lo:[0,1] neg_hi:[0,1]
	s_nop 0
	v_add_f32_e32 v3, v11, v3
	v_add_f32_e32 v2, v2, v3
	v_add_f32_e32 v3, v15, v14
	v_add_f32_e32 v2, v5, v2
	v_sub_f32_e32 v4, v3, v15
	v_mul_f32_e32 v2, v13, v2
	v_sub_f32_e32 v4, v14, v4
	v_add_f32_e32 v4, v4, v2
	v_add_f32_e32 v6, v3, v4
	v_mul_f32_e32 v7, v6, v6
	v_fmamk_f32 v2, v7, 0x3e9b6dac, v212
	v_fmaak_f32 v177, v7, v2, 0x3f2aaada
	v_cvt_f32_i32_e32 v2, v10
	v_sub_f32_e32 v3, v6, v3
	v_sub_f32_e32 v3, v4, v3
	v_ldexp_f32 v8, v3, 1
	v_mul_f32_e32 v3, v6, v7
	v_ldexp_f32 v5, v6, 1
	v_pk_mul_f32 v[6:7], v[2:3], v[176:177]
	s_nop 0
	v_fma_f32 v4, v2, s66, -v6
	v_fmac_f32_e32 v4, 0xb102e308, v2
	v_pk_add_f32 v[2:3], v[6:7], v[4:5]
	s_mov_b32 s66, 0x7f800000
	v_sub_f32_e32 v5, v3, v5
	v_sub_f32_e32 v5, v7, v5
	v_add_f32_e32 v9, v8, v5
	v_mov_b32_e32 v8, v6
	v_pk_add_f32 v[6:7], v[2:3], v[6:7] neg_lo:[0,1] neg_hi:[0,1]
	v_pk_add_f32 v[10:11], v[2:3], v[8:9]
	v_mov_b32_e32 v5, v2
	v_mov_b32_e32 v7, v11
	v_pk_add_f32 v[12:13], v[4:5], v[6:7] neg_lo:[0,1] neg_hi:[0,1]
	v_pk_add_f32 v[4:5], v[4:5], v[6:7]
	v_mov_b32_e32 v8, v9
	v_pk_add_f32 v[6:7], v[4:5], v[2:3] op_sel:[1,0] op_sel_hi:[0,1] neg_lo:[0,1] neg_hi:[0,1]
	v_pk_add_f32 v[14:15], v[10:11], v[6:7] op_sel_hi:[1,0] neg_lo:[0,1] neg_hi:[0,1]
	v_mov_b32_e32 v10, v11
	v_mov_b32_e32 v11, v5
	v_pk_mov_b32 v[6:7], v[2:3], v[6:7] op_sel:[1,0]
	v_mov_b32_e32 v9, v2
	v_pk_add_f32 v[6:7], v[10:11], v[6:7] neg_lo:[0,1] neg_hi:[0,1]
	v_mov_b32_e32 v14, v12
	v_pk_add_f32 v[2:3], v[8:9], v[6:7] neg_lo:[0,1] neg_hi:[0,1]
	v_mov_b32_e32 v13, v5
	v_pk_add_f32 v[6:7], v[14:15], v[2:3]
	v_cmp_neq_f32_e32 vcc, s66, v16
	v_pk_add_f32 v[8:9], v[6:7], v[6:7] op_sel:[0,1] op_sel_hi:[1,0]
	s_mov_b32 s66, 0x33800000
	v_pk_add_f32 v[4:5], v[4:5], v[8:9] op_sel:[1,0] op_sel_hi:[0,1]
	v_mov_b32_e32 v7, v4
	v_pk_add_f32 v[10:11], v[6:7], v[12:13] neg_lo:[0,1] neg_hi:[0,1]
	v_mov_b32_e32 v3, v8
	v_sub_f32_e32 v5, v6, v10
	v_pk_add_f32 v[2:3], v[2:3], v[10:11] neg_lo:[0,1] neg_hi:[0,1]
	v_sub_f32_e32 v5, v12, v5
	v_add_f32_e32 v2, v2, v5
	v_add_f32_e32 v2, v2, v3
	v_add_f32_e32 v2, v4, v2
	v_cndmask_b32_e32 v2, v215, v2, vcc
	v_cmp_lt_f32_e64 vcc, |v16|, s66
	s_nop 1
	v_cndmask_b32_e32 v3, v2, v16, vcc
